# final RMSNorm phase rewritten by hand: final_g hoisted out of the row loop, all 8 row loads in flight, double-buffered rows, no waits between stores
# speedup vs baseline: 1.0001x; 1.0001x over previous
; __device__ __forceinline__ void ph_final(const Args& a, const Frame& F, float* dst = nullptr) {
;     int tid = threadIdx.x; asm volatile("" : "+v"(tid)); int lane = tid & 63; (void)lane;
;     const int gw = F.vcu * NWAVES + F.wave, NGW = F.G * NWAVES; const f32x4* gr = (const f32x4*)a.in[I_FING] + lane;
;     for (int m0 = gw; m0 < NTOK; m0 += 2 * NGW) {
;         f32x4 v[2][8];
; #pragma unroll
;         for (int r = 0; r < 2; ++r) { const int m = m0 + r * NGW; const f32x4* xr = (const f32x4*)(a.out + (size_t)(m < NTOK ? m : m0) * DM) + lane;
; #pragma unroll
;             for (int j = 0; j < 8; ++j) v[r][j] = xr[64 * j]; }
.LBB0_1293:
	v_readlane_b32 s2, v250, 10
	v_readlane_b32 s3, v250, 11
	s_cmp_lt_i32 s2, 57
	s_cselect_b64 s[0:1], -1, 0
	s_cmp_gt_i32 s3, 56
	s_cselect_b64 s[2:3], -1, 0
	s_and_b64 s[0:1], s[0:1], s[2:3]
	s_and_b64 vcc, exec, s[0:1]
	s_cbranch_vccz .LBB0_1299
	v_readlane_b32 s0, v252, 57
	v_readlane_b32 s1, v252, 58
	s_andn2_b64 vcc, exec, s[0:1]
	s_cbranch_vccnz .LBB0_1299
	v_and_b32_e32 v0, 63, v0
	v_readlane_b32 s0, v250, 0
	v_lshlrev_b32_e32 v0, 4, v0
	v_mov_b32_e32 v1, 0
	v_readlane_b32 s6, v250, 6
	v_readlane_b32 s7, v250, 7
	v_lshl_add_u64 v[42:43], s[88:89], 0, v[0:1]
	v_readlane_b32 s1, v250, 1
	v_lshl_add_u64 v[40:41], s[6:7], 0, v[0:1]
	v_and_b32_e32 v0, 64, v224
	v_add_u32_e32 v0, 64, v0
	v_xor_b32_e32 v1, 1, v224
	v_cmp_lt_i32_e32 vcc, v1, v0
	s_mov_b64 s[0:1], 0x1000
	v_lshl_add_u64 v[44:45], v[40:41], 0, s[0:1]
	v_cndmask_b32_e32 v1, v224, v1, vcc
	v_lshlrev_b32_e32 v56, 2, v1
	v_xor_b32_e32 v1, 2, v224
	v_cmp_lt_i32_e32 vcc, v1, v0
	s_mov_b64 s[0:1], 0x1400
	v_lshl_add_u64 v[46:47], v[40:41], 0, s[0:1]
	v_cndmask_b32_e32 v1, v224, v1, vcc
	v_lshlrev_b32_e32 v57, 2, v1
	v_xor_b32_e32 v1, 4, v224
	v_cmp_lt_i32_e32 vcc, v1, v0
	s_mov_b64 s[0:1], 0x1800
	v_readlane_b32 s4, v250, 4
	v_cndmask_b32_e32 v1, v224, v1, vcc
	v_lshlrev_b32_e32 v58, 2, v1
	v_xor_b32_e32 v1, 8, v224
	v_cmp_lt_i32_e32 vcc, v1, v0
	v_readlane_b32 s5, v250, 5
	v_lshl_add_u64 v[48:49], v[40:41], 0, s[0:1]
	v_cndmask_b32_e32 v1, v224, v1, vcc
	v_lshlrev_b32_e32 v59, 2, v1
	v_xor_b32_e32 v1, 16, v224
	v_cmp_lt_i32_e32 vcc, v1, v0
	s_mov_b64 s[0:1], 0x1c00
	v_lshl_add_u64 v[50:51], v[40:41], 0, s[0:1]
	v_cndmask_b32_e32 v1, v224, v1, vcc
	v_lshlrev_b32_e32 v60, 2, v1
	v_xor_b32_e32 v1, 32, v224
	v_cmp_lt_i32_e32 vcc, v1, v0
	s_movk_i32 s4, 0x1000
	v_mov_b32_e32 v62, 0x358637bd
	v_cndmask_b32_e32 v0, v224, v1, vcc
	v_lshlrev_b32_e32 v61, 2, v0
	s_mov_b32 s5, 0xf800000
	v_mov_b32_e32 v63, 0x260
	v_readlane_b32 s2, v250, 2
	v_readlane_b32 s3, v250, 3
	v_readlane_b32 s6, v249, 33
	v_readlane_b32 s7, v249, 35
	s_mov_b64 s[10:11], 0x1000
	global_load_dwordx4 v[84:87], v[40:41], off
	global_load_dwordx4 v[88:91], v[40:41], off offset:1024
	global_load_dwordx4 v[92:95], v[40:41], off offset:2048
	global_load_dwordx4 v[96:99], v[40:41], off offset:3072
	global_load_dwordx4 v[100:103], v[44:45], off
	global_load_dwordx4 v[104:107], v[46:47], off
	global_load_dwordx4 v[108:111], v[48:49], off
	global_load_dwordx4 v[112:115], v[50:51], off
	s_cmp_lt_i32 s6, 0xa000
	s_cbranch_scc0 .LBB0_1299
	s_ashr_i32 s1, s6, 31
	s_mov_b32 s0, s6
	s_lshl_b64 s[0:1], s[0:1], 13
	v_lshl_add_u64 v[52:53], v[42:43], 0, s[0:1]
	v_lshl_add_u64 v[54:55], v[52:53], 0, s[10:11]
	global_load_dwordx4 v[116:119], v[52:53], off
	global_load_dwordx4 v[120:123], v[52:53], off offset:1024
	global_load_dwordx4 v[124:127], v[52:53], off offset:2048
	global_load_dwordx4 v[128:131], v[52:53], off offset:3072
	global_load_dwordx4 v[132:135], v[54:55], off
	global_load_dwordx4 v[136:139], v[54:55], off offset:1024
	global_load_dwordx4 v[140:143], v[54:55], off offset:2048
	global_load_dwordx4 v[144:147], v[54:55], off offset:3072
	s_add_i32 s8, s6, s7
	s_cmp_lt_i32 s8, 0xa000
	s_cbranch_scc0 .Lfin_no_l1
	s_ashr_i32 s1, s8, 31
	s_mov_b32 s0, s8
	s_lshl_b64 s[0:1], s[0:1], 13
	v_lshl_add_u64 v[64:65], v[42:43], 0, s[0:1]
	v_lshl_add_u64 v[66:67], v[64:65], 0, s[10:11]
	global_load_dwordx4 v[148:151], v[64:65], off
	global_load_dwordx4 v[152:155], v[64:65], off offset:1024
	global_load_dwordx4 v[156:159], v[64:65], off offset:2048
	global_load_dwordx4 v[160:163], v[64:65], off offset:3072
	global_load_dwordx4 v[164:167], v[66:67], off
	global_load_dwordx4 v[168:171], v[66:67], off offset:1024
	global_load_dwordx4 v[172:175], v[66:67], off offset:2048
	global_load_dwordx4 v[176:179], v[66:67], off offset:3072

; __device__ __forceinline__ void ph_final(const Args& a, const Frame& F, float* dst = nullptr) {
;     ...
;         for (int r = 0; r < 2; ++r) { const int m = m0 + r * NGW; float sq = 0.f;
; #pragma unroll
;             for (int j = 0; j < 8; ++j) sq += (v[r][j].x * v[r][j].x + v[r][j].y * v[r][j].y) + (v[r][j].z * v[r][j].z + v[r][j].w * v[r][j].w);
;             const float rstd = 1.f / sqrtf(wave_sum(sq) * (1.f / DM) + EPS);
;             if (m < NTOK) { f32x4* xo = (dst ? (f32x4*)(dst + (size_t)m * DM) : (f32x4*)(a.out + (size_t)m * DM)) + lane;
; #pragma unroll
;                 for (int j = 0; j < 8; ++j) xo[64 * j] = v[r][j] * rstd * gr[64 * j]; } }
.Lfin_b0:
	s_waitcnt vmcnt(8)
	v_mul_f32_e32 v2, v117, v117
	v_mul_f32_e32 v3, v119, v119
	v_fmac_f32_e32 v2, v116, v116
	v_fmac_f32_e32 v3, v118, v118
	v_add_f32_e32 v2, v2, v3
	v_mov_b32_e32 v12, v2
	v_mul_f32_e32 v2, v121, v121
	v_mul_f32_e32 v3, v123, v123
	v_fmac_f32_e32 v2, v120, v120
	v_fmac_f32_e32 v3, v122, v122
	v_add_f32_e32 v2, v2, v3
	v_add_f32_e32 v12, v12, v2
	v_mul_f32_e32 v2, v125, v125
	v_mul_f32_e32 v3, v127, v127
	v_fmac_f32_e32 v2, v124, v124
	v_fmac_f32_e32 v3, v126, v126
	v_add_f32_e32 v2, v2, v3
	v_add_f32_e32 v12, v12, v2
	v_mul_f32_e32 v2, v129, v129
	v_mul_f32_e32 v3, v131, v131
	v_fmac_f32_e32 v2, v128, v128
	v_fmac_f32_e32 v3, v130, v130
	v_add_f32_e32 v2, v2, v3
	v_add_f32_e32 v12, v12, v2
	v_mul_f32_e32 v2, v133, v133
	v_mul_f32_e32 v3, v135, v135
	v_fmac_f32_e32 v2, v132, v132
	v_fmac_f32_e32 v3, v134, v134
	v_add_f32_e32 v2, v2, v3
	v_add_f32_e32 v12, v12, v2
	v_mul_f32_e32 v2, v137, v137
	v_mul_f32_e32 v3, v139, v139
	v_fmac_f32_e32 v2, v136, v136
	v_fmac_f32_e32 v3, v138, v138
	v_add_f32_e32 v2, v2, v3
	v_add_f32_e32 v12, v12, v2
	v_mul_f32_e32 v2, v141, v141
	v_mul_f32_e32 v3, v143, v143
	v_fmac_f32_e32 v2, v140, v140
	v_fmac_f32_e32 v3, v142, v142
	v_add_f32_e32 v2, v2, v3
	v_add_f32_e32 v12, v12, v2
	v_mul_f32_e32 v2, v145, v145
	v_mul_f32_e32 v3, v147, v147
	v_fmac_f32_e32 v2, v144, v144
	v_fmac_f32_e32 v3, v146, v146
	v_add_f32_e32 v2, v2, v3
	v_add_f32_e32 v12, v12, v2
	ds_bpermute_b32 v13, v56, v12
	s_waitcnt lgkmcnt(0)
	v_add_f32_e32 v12, v12, v13
	ds_bpermute_b32 v13, v57, v12
	s_waitcnt lgkmcnt(0)
	v_add_f32_e32 v12, v12, v13
	ds_bpermute_b32 v13, v58, v12
	s_waitcnt lgkmcnt(0)
	v_add_f32_e32 v12, v12, v13
	ds_bpermute_b32 v13, v59, v12
	s_waitcnt lgkmcnt(0)
	v_add_f32_e32 v12, v12, v13
	ds_bpermute_b32 v13, v60, v12
	s_waitcnt lgkmcnt(0)
	v_add_f32_e32 v12, v12, v13
	ds_bpermute_b32 v13, v61, v12
	s_waitcnt lgkmcnt(0)
	v_add_f32_e32 v12, v12, v13
	v_fmamk_f32 v12, v12, 0x3a000000, v62
	v_mul_f32_e32 v13, 0x4f800000, v12
	v_cmp_gt_f32_e32 vcc, s5, v12
	s_nop 1
	v_cndmask_b32_e32 v12, v12, v13, vcc
	v_sqrt_f32_e32 v13, v12
	s_nop 0
	v_add_u32_e32 v14, -1, v13
	v_add_u32_e32 v15, 1, v13
	v_fma_f32 v28, -v14, v13, v12
	v_fma_f32 v29, -v15, v13, v12
	v_cmp_ge_f32_e64 s[0:1], 0, v28
	s_nop 1
	v_cndmask_b32_e64 v13, v13, v14, s[0:1]
	v_cmp_lt_f32_e64 s[0:1], 0, v29
	s_nop 1
	v_cndmask_b32_e64 v13, v13, v15, s[0:1]
	v_mul_f32_e32 v14, 0x37800000, v13
	v_cndmask_b32_e32 v13, v13, v14, vcc
	v_cmp_class_f32_e32 vcc, v12, v63
	s_nop 1
	v_cndmask_b32_e32 v70, v13, v12, vcc
	v_div_scale_f32 v71, s[0:1], v70, v70, 1.0
	v_rcp_f32_e32 v72, v71
	v_div_scale_f32 v73, vcc, 1.0, v70, 1.0
	v_fma_f32 v74, -v71, v72, 1.0
	v_fmac_f32_e32 v72, v74, v72
	v_mul_f32_e32 v74, v73, v72
	v_fma_f32 v75, -v71, v74, v73
	v_fmac_f32_e32 v74, v75, v72
	v_fma_f32 v71, -v71, v74, v73
	v_div_fmas_f32 v71, v71, v72, v74
	v_div_fixup_f32 v70, v71, v70, 1.0
	s_nop 0
	v_pk_mul_f32 v[116:117], v[116:117], v[70:71] op_sel_hi:[1,0]
	v_pk_mul_f32 v[118:119], v[118:119], v[70:71] op_sel_hi:[1,0]
	v_pk_mul_f32 v[120:121], v[120:121], v[70:71] op_sel_hi:[1,0]
	v_pk_mul_f32 v[122:123], v[122:123], v[70:71] op_sel_hi:[1,0]
	v_pk_mul_f32 v[124:125], v[124:125], v[70:71] op_sel_hi:[1,0]
	v_pk_mul_f32 v[126:127], v[126:127], v[70:71] op_sel_hi:[1,0]
	v_pk_mul_f32 v[128:129], v[128:129], v[70:71] op_sel_hi:[1,0]
	v_pk_mul_f32 v[130:131], v[130:131], v[70:71] op_sel_hi:[1,0]
	v_pk_mul_f32 v[132:133], v[132:133], v[70:71] op_sel_hi:[1,0]
	v_pk_mul_f32 v[134:135], v[134:135], v[70:71] op_sel_hi:[1,0]
	v_pk_mul_f32 v[136:137], v[136:137], v[70:71] op_sel_hi:[1,0]
	v_pk_mul_f32 v[138:139], v[138:139], v[70:71] op_sel_hi:[1,0]
	v_pk_mul_f32 v[140:141], v[140:141], v[70:71] op_sel_hi:[1,0]
	v_pk_mul_f32 v[142:143], v[142:143], v[70:71] op_sel_hi:[1,0]
	v_pk_mul_f32 v[144:145], v[144:145], v[70:71] op_sel_hi:[1,0]
	v_pk_mul_f32 v[146:147], v[146:147], v[70:71] op_sel_hi:[1,0]
	v_pk_mul_f32 v[116:117], v[84:85], v[116:117]
	v_pk_mul_f32 v[118:119], v[86:87], v[118:119]
	v_pk_mul_f32 v[120:121], v[88:89], v[120:121]
	v_pk_mul_f32 v[122:123], v[90:91], v[122:123]
	v_pk_mul_f32 v[124:125], v[92:93], v[124:125]
	v_pk_mul_f32 v[126:127], v[94:95], v[126:127]
	v_pk_mul_f32 v[128:129], v[96:97], v[128:129]
	v_pk_mul_f32 v[130:131], v[98:99], v[130:131]
	v_pk_mul_f32 v[132:133], v[100:101], v[132:133]
	v_pk_mul_f32 v[134:135], v[102:103], v[134:135]
	v_pk_mul_f32 v[136:137], v[104:105], v[136:137]
	v_pk_mul_f32 v[138:139], v[106:107], v[138:139]
	v_pk_mul_f32 v[140:141], v[108:109], v[140:141]
	v_pk_mul_f32 v[142:143], v[110:111], v[142:143]
	v_pk_mul_f32 v[144:145], v[112:113], v[144:145]
	v_pk_mul_f32 v[146:147], v[114:115], v[146:147]
	global_store_dwordx4 v[52:53], v[116:119], off
	global_store_dwordx4 v[52:53], v[120:123], off offset:1024
	global_store_dwordx4 v[52:53], v[124:127], off offset:2048
	global_store_dwordx4 v[52:53], v[128:131], off offset:3072
	global_store_dwordx4 v[54:55], v[132:135], off
	global_store_dwordx4 v[54:55], v[136:139], off offset:1024
	global_store_dwordx4 v[54:55], v[140:143], off offset:2048
	global_store_dwordx4 v[54:55], v[144:147], off offset:3072
	s_add_i32 s9, s8, s7
	s_cmp_lt_i32 s9, 0xa000
	s_cbranch_scc0 .Lfin_b0_nl
	s_ashr_i32 s1, s9, 31
	s_mov_b32 s0, s9
	s_lshl_b64 s[0:1], s[0:1], 13
	v_lshl_add_u64 v[52:53], v[42:43], 0, s[0:1]
	v_lshl_add_u64 v[54:55], v[52:53], 0, s[10:11]
	global_load_dwordx4 v[116:119], v[52:53], off
	global_load_dwordx4 v[120:123], v[52:53], off offset:1024
	global_load_dwordx4 v[124:127], v[52:53], off offset:2048
	global_load_dwordx4 v[128:131], v[52:53], off offset:3072
	global_load_dwordx4 v[132:135], v[54:55], off
	global_load_dwordx4 v[136:139], v[54:55], off offset:1024
	global_load_dwordx4 v[140:143], v[54:55], off offset:2048
	global_load_dwordx4 v[144:147], v[54:55], off offset:3072
; __device__ __forceinline__ void ph_final(const Args& a, const Frame& F, float* dst = nullptr) {
;     ...
;         for (int r = 0; r < 2; ++r) { const int m = m0 + r * NGW; float sq = 0.f;
; #pragma unroll
;             for (int j = 0; j < 8; ++j) sq += (v[r][j].x * v[r][j].x + v[r][j].y * v[r][j].y) + (v[r][j].z * v[r][j].z + v[r][j].w * v[r][j].w);
;             const float rstd = 1.f / sqrtf(wave_sum(sq) * (1.f / DM) + EPS);
;             if (m < NTOK) { f32x4* xo = (dst ? (f32x4*)(dst + (size_t)m * DM) : (f32x4*)(a.out + (size_t)m * DM)) + lane;
; #pragma unroll
;                 for (int j = 0; j < 8; ++j) xo[64 * j] = v[r][j] * rstd * gr[64 * j]; } }
.Lfin_b0_nl:
	s_cmp_lt_i32 s8, 0xa000
	s_cbranch_scc0 .LBB0_1299
	s_waitcnt vmcnt(8)
	v_mul_f32_e32 v2, v149, v149
	v_mul_f32_e32 v3, v151, v151
	v_fmac_f32_e32 v2, v148, v148
	v_fmac_f32_e32 v3, v150, v150
	v_add_f32_e32 v2, v2, v3
	v_mov_b32_e32 v12, v2
	v_mul_f32_e32 v2, v153, v153
	v_mul_f32_e32 v3, v155, v155
	v_fmac_f32_e32 v2, v152, v152
	v_fmac_f32_e32 v3, v154, v154
	v_add_f32_e32 v2, v2, v3
	v_add_f32_e32 v12, v12, v2
	v_mul_f32_e32 v2, v157, v157
	v_mul_f32_e32 v3, v159, v159
	v_fmac_f32_e32 v2, v156, v156
	v_fmac_f32_e32 v3, v158, v158
	v_add_f32_e32 v2, v2, v3
	v_add_f32_e32 v12, v12, v2
	v_mul_f32_e32 v2, v161, v161
	v_mul_f32_e32 v3, v163, v163
	v_fmac_f32_e32 v2, v160, v160
	v_fmac_f32_e32 v3, v162, v162
	v_add_f32_e32 v2, v2, v3
	v_add_f32_e32 v12, v12, v2
	v_mul_f32_e32 v2, v165, v165
	v_mul_f32_e32 v3, v167, v167
	v_fmac_f32_e32 v2, v164, v164
	v_fmac_f32_e32 v3, v166, v166
	v_add_f32_e32 v2, v2, v3
	v_add_f32_e32 v12, v12, v2
	v_mul_f32_e32 v2, v169, v169
	v_mul_f32_e32 v3, v171, v171
	v_fmac_f32_e32 v2, v168, v168
	v_fmac_f32_e32 v3, v170, v170
	v_add_f32_e32 v2, v2, v3
	v_add_f32_e32 v12, v12, v2
	v_mul_f32_e32 v2, v173, v173
	v_mul_f32_e32 v3, v175, v175
	v_fmac_f32_e32 v2, v172, v172
	v_fmac_f32_e32 v3, v174, v174
	v_add_f32_e32 v2, v2, v3
	v_add_f32_e32 v12, v12, v2
	v_mul_f32_e32 v2, v177, v177
	v_mul_f32_e32 v3, v179, v179
	v_fmac_f32_e32 v2, v176, v176
	v_fmac_f32_e32 v3, v178, v178
	v_add_f32_e32 v2, v2, v3
	v_add_f32_e32 v12, v12, v2
	ds_bpermute_b32 v13, v56, v12
	s_waitcnt lgkmcnt(0)
	v_add_f32_e32 v12, v12, v13
	ds_bpermute_b32 v13, v57, v12
	s_waitcnt lgkmcnt(0)
	v_add_f32_e32 v12, v12, v13
	ds_bpermute_b32 v13, v58, v12
	s_waitcnt lgkmcnt(0)
	v_add_f32_e32 v12, v12, v13
	ds_bpermute_b32 v13, v59, v12
	s_waitcnt lgkmcnt(0)
	v_add_f32_e32 v12, v12, v13
	ds_bpermute_b32 v13, v60, v12
	s_waitcnt lgkmcnt(0)
	v_add_f32_e32 v12, v12, v13
	ds_bpermute_b32 v13, v61, v12
	s_waitcnt lgkmcnt(0)
	v_add_f32_e32 v12, v12, v13
	v_fmamk_f32 v12, v12, 0x3a000000, v62
	v_mul_f32_e32 v13, 0x4f800000, v12
	v_cmp_gt_f32_e32 vcc, s5, v12
	s_nop 1
	v_cndmask_b32_e32 v12, v12, v13, vcc
	v_sqrt_f32_e32 v13, v12
	s_nop 0
	v_add_u32_e32 v14, -1, v13
	v_add_u32_e32 v15, 1, v13
	v_fma_f32 v28, -v14, v13, v12
	v_fma_f32 v29, -v15, v13, v12
	v_cmp_ge_f32_e64 s[0:1], 0, v28
	s_nop 1
	v_cndmask_b32_e64 v13, v13, v14, s[0:1]
	v_cmp_lt_f32_e64 s[0:1], 0, v29
	s_nop 1
	v_cndmask_b32_e64 v13, v13, v15, s[0:1]
	v_mul_f32_e32 v14, 0x37800000, v13
	v_cndmask_b32_e32 v13, v13, v14, vcc
	v_cmp_class_f32_e32 vcc, v12, v63
	s_nop 1
	v_cndmask_b32_e32 v70, v13, v12, vcc
	v_div_scale_f32 v71, s[0:1], v70, v70, 1.0
	v_rcp_f32_e32 v72, v71
	v_div_scale_f32 v73, vcc, 1.0, v70, 1.0
	v_fma_f32 v74, -v71, v72, 1.0
	v_fmac_f32_e32 v72, v74, v72
	v_mul_f32_e32 v74, v73, v72
	v_fma_f32 v75, -v71, v74, v73
	v_fmac_f32_e32 v74, v75, v72
	v_fma_f32 v71, -v71, v74, v73
	v_div_fmas_f32 v71, v71, v72, v74
	v_div_fixup_f32 v70, v71, v70, 1.0
	s_nop 0
	v_pk_mul_f32 v[148:149], v[148:149], v[70:71] op_sel_hi:[1,0]
	v_pk_mul_f32 v[150:151], v[150:151], v[70:71] op_sel_hi:[1,0]
	v_pk_mul_f32 v[152:153], v[152:153], v[70:71] op_sel_hi:[1,0]
	v_pk_mul_f32 v[154:155], v[154:155], v[70:71] op_sel_hi:[1,0]
	v_pk_mul_f32 v[156:157], v[156:157], v[70:71] op_sel_hi:[1,0]
	v_pk_mul_f32 v[158:159], v[158:159], v[70:71] op_sel_hi:[1,0]
	v_pk_mul_f32 v[160:161], v[160:161], v[70:71] op_sel_hi:[1,0]
	v_pk_mul_f32 v[162:163], v[162:163], v[70:71] op_sel_hi:[1,0]
	v_pk_mul_f32 v[164:165], v[164:165], v[70:71] op_sel_hi:[1,0]
	v_pk_mul_f32 v[166:167], v[166:167], v[70:71] op_sel_hi:[1,0]
	v_pk_mul_f32 v[168:169], v[168:169], v[70:71] op_sel_hi:[1,0]
	v_pk_mul_f32 v[170:171], v[170:171], v[70:71] op_sel_hi:[1,0]
	v_pk_mul_f32 v[172:173], v[172:173], v[70:71] op_sel_hi:[1,0]
	v_pk_mul_f32 v[174:175], v[174:175], v[70:71] op_sel_hi:[1,0]
	v_pk_mul_f32 v[176:177], v[176:177], v[70:71] op_sel_hi:[1,0]
	v_pk_mul_f32 v[178:179], v[178:179], v[70:71] op_sel_hi:[1,0]
	v_pk_mul_f32 v[148:149], v[84:85], v[148:149]
	v_pk_mul_f32 v[150:151], v[86:87], v[150:151]
	v_pk_mul_f32 v[152:153], v[88:89], v[152:153]
	v_pk_mul_f32 v[154:155], v[90:91], v[154:155]
	v_pk_mul_f32 v[156:157], v[92:93], v[156:157]
	v_pk_mul_f32 v[158:159], v[94:95], v[158:159]
	v_pk_mul_f32 v[160:161], v[96:97], v[160:161]
	v_pk_mul_f32 v[162:163], v[98:99], v[162:163]
	v_pk_mul_f32 v[164:165], v[100:101], v[164:165]
	v_pk_mul_f32 v[166:167], v[102:103], v[166:167]
	v_pk_mul_f32 v[168:169], v[104:105], v[168:169]
	v_pk_mul_f32 v[170:171], v[106:107], v[170:171]
	v_pk_mul_f32 v[172:173], v[108:109], v[172:173]
	v_pk_mul_f32 v[174:175], v[110:111], v[174:175]
	v_pk_mul_f32 v[176:177], v[112:113], v[176:177]
	v_pk_mul_f32 v[178:179], v[114:115], v[178:179]
	global_store_dwordx4 v[64:65], v[148:151], off
	global_store_dwordx4 v[64:65], v[152:155], off offset:1024
	global_store_dwordx4 v[64:65], v[156:159], off offset:2048
	global_store_dwordx4 v[64:65], v[160:163], off offset:3072
	global_store_dwordx4 v[66:67], v[164:167], off
	global_store_dwordx4 v[66:67], v[168:171], off offset:1024
	global_store_dwordx4 v[66:67], v[172:175], off offset:2048
	global_store_dwordx4 v[66:67], v[176:179], off offset:3072
	s_add_i32 s6, s9, s7
	s_cmp_lt_i32 s6, 0xa000
	s_cbranch_scc0 .Lfin_b1_nl
	s_ashr_i32 s1, s6, 31
	s_mov_b32 s0, s6
	s_lshl_b64 s[0:1], s[0:1], 13
	v_lshl_add_u64 v[64:65], v[42:43], 0, s[0:1]
	v_lshl_add_u64 v[66:67], v[64:65], 0, s[10:11]
	global_load_dwordx4 v[148:151], v[64:65], off
	global_load_dwordx4 v[152:155], v[64:65], off offset:1024
	global_load_dwordx4 v[156:159], v[64:65], off offset:2048
	global_load_dwordx4 v[160:163], v[64:65], off offset:3072
	global_load_dwordx4 v[164:167], v[66:67], off
	global_load_dwordx4 v[168:171], v[66:67], off offset:1024
	global_load_dwordx4 v[172:175], v[66:67], off offset:2048
	global_load_dwordx4 v[176:179], v[66:67], off offset:3072
.Lfin_b1_nl:
	s_mov_b32 s8, s6
	s_mov_b32 s6, s9
	s_cmp_lt_i32 s6, 0xa000
	s_cbranch_scc1 .Lfin_b0
